# phase 3: the S5 prompt prefix requests both halves of its segment coefficient together (one drain fewer per item)
# speedup vs baseline: 1.0004x; 1.0004x over previous
; DEVINL void s5_passC_prompt(const Params& p, char* smem, int item) {
;     ...
;   const int bq = item >> 3, s = item & 7, b = bq >> 3, g = (bq & 7) * 4 + wid;
;   const int bg = b * 32 + g;
;   int rb, ntok; seg_rows(b, s, rb, ntok);
;   float hr = 0.f, hi = 0.f;
;   const float4 pw = ((const float4*)(p.ws + OFF_APW))[g * 64 + lane];
;   const float2* hend = (const float2*)(p.ws + OFF_HEND);
;   for (int s2 = 0; s2 < s; ++s2) {
;     float pr = (s2 == 0) ? pw.z : pw.x, pi = (s2 == 0) ? pw.w : pw.y;
;     float2 he = hend[((size_t)bg * 7 + s2) * 64 + lane];
;     float nr = pr * hr - pi * hi + he.x, ni = pr * hi + pi * hr + he.y;
;     hr = nr; hi = ni;
;   }
.LBB0_493:
	v_mov_b32_e32 v3, v0
	s_waitcnt lgkmcnt(0)
	s_barrier
	v_ashrrev_i32_e32 v58, 6, v79
	v_and_b32_e32 v80, 63, v3
	v_mov_b32_e32 v3, v0
	v_and_b32_e32 v63, 7, v79
	v_ashrrev_i32_e32 v68, 6, v3
	v_lshrrev_b32_e32 v3, 1, v79
	v_and_b32_e32 v10, 28, v3
	v_add_u32_e32 v4, v68, v10
	v_lshlrev_b32_e32 v11, 5, v58
	v_mov_b32_e32 v3, v2
	v_add_u32_e32 v62, v4, v11
	v_cmp_eq_u32_e64 s[34:35], 0, v63
	v_cmp_ne_u32_e32 vcc, 0, v63
	v_lshlrev_b32_e32 v5, 6, v4
	v_mov_b64_e32 v[66:67], v[2:3]
	s_and_saveexec_b64 s[36:37], vcc
	s_cbranch_execz .LBB0_499
	v_or_b32_e32 v6, v5, v80
	v_readlane_b32 s0, v194, 51
	v_ashrrev_i32_e32 v7, 31, v6
	v_readlane_b32 s1, v194, 52
	v_lshlrev_b32_e32 v12, 3, v80
	v_mov_b32_e32 v13, v2
	v_lshl_add_u64 v[6:7], v[6:7], 4, s[0:1]
	v_readlane_b32 s0, v194, 53
	v_readlane_b32 s1, v194, 54
	global_load_dwordx2 v[8:9], v[6:7], off offset:8
	global_load_dwordx2 v[216:217], v[6:7], off
	v_cmp_ne_u32_e32 vcc, 1, v63
	v_lshl_add_u64 v[12:13], s[0:1], 0, v[12:13]
	s_movk_i32 s0, 0xe00
	v_mad_i64_i32 v[12:13], s[0:1], v62, s0, v[12:13]
	global_load_dwordx2 v[204:205], v[12:13], off offset:512
	global_load_dwordx2 v[206:207], v[12:13], off offset:1024
	global_load_dwordx2 v[208:209], v[12:13], off offset:1536
	global_load_dwordx2 v[210:211], v[12:13], off offset:2048
	global_load_dwordx2 v[212:213], v[12:13], off offset:2560
	global_load_dwordx2 v[214:215], v[12:13], off offset:3072
	global_load_dwordx2 v[12:13], v[12:13], off
	s_waitcnt vmcnt(1)
	v_mul_f32_e32 v3, 0, v8
	v_mul_f32_e32 v15, 0, v9
	v_sub_f32_e32 v14, v3, v15
	v_fmac_f32_e32 v15, 0, v8
	s_waitcnt vmcnt(0)
	v_pk_add_f32 v[66:67], v[12:13], v[14:15]
	s_and_saveexec_b64 s[38:39], vcc
	s_cbranch_execz .LBB0_498
	v_mov_b64_e32 v[6:7], v[216:217]
	v_add3_u32 v10, v68, v11, v10
	s_movk_i32 s0, 0xe00
	v_mad_i64_i32 v[10:11], s[0:1], v10, s0, 0
	v_readlane_b32 s0, v192, 27
	v_and_b32_e32 v3, 7, v75
	v_lshl_or_b32 v10, v80, 3, v10
	v_readlane_b32 s1, v192, 28
	v_add_u32_e32 v3, -1, v3
	v_mov_b32_e32 v12, v67
	v_lshl_add_u64 v[10:11], s[0:1], 0, v[10:11]
	s_mov_b64 s[0:1], 0
	s_waitcnt vmcnt(0)
	v_pk_mov_b32 v[8:9], v[6:7], v[6:7] op_sel:[1,0]
